# v42 plus w_in epilogue weight vector read from LDS (DMA once per phase) in the retention layers
# baseline (speedup 1.0000x reference)
;     __device__ bool next(int i, Unit& u) const { if (i > 0) return false; const int t = c - first; if (t < 0 || t >= nM * nN) return false; u.pm = t % nM; u.pn = t / nM; return true; }
; #define PG8_STAGE(bufoff, gbase, voff) do { _Pragma("unroll") for (int _i = 0; _i < 2; ++_i) \
;         __builtin_amdgcn_global_load_lds((const unsigned*)((const char*)(gbase) + (voff)[_i]), (PG8_LAS unsigned*)(lds + (bufoff) + ldsw + _i * 8192), 16, 0, 0); } while (0)
; #define PG8_WAIT_V(n) asm volatile("s_waitcnt vmcnt(" #n ")" ::: "memory")
; #define PG8_BAR __builtin_amdgcn_s_barrier()
;     __device__ __forceinline__ void operator()(const f32x4 (&acc)[2][2][4][2], const Unit& u, int wr, int wc, int fr, int fq) const {
;     ...
;             for (int n = 0; n < 2; ++n) wv[bj][n] = *(const f32x4*)(w + 32 * bj + 8 * fq + 4 * n) * nsc;
; template <class Epi, class Sched, bool ALIGN_EPI = false, bool SP2 = false>
; __device__ __forceinline__ void gemm_phase(PG8_LAS unsigned char* lds, const Gemm g, const Sched& S, const Epi& E, int tid_in) {
;     ...
;     const int aoff = lds_byte(wr * 64 + fr, fq * 8), boff = lds_byte(wc * 32 + fr, fq * 8);
;     ...
;     Unit cur, nxt; int ui = 0;
;     if (!S.next(0, cur)) return;
;     f32x4 acc[2][2][4][2];
; #pragma unroll
;     for (int a = 0; a < 2; ++a)
; #pragma unroll
;         for (int b = 0; b < 2; ++b)
; #pragma unroll
;             for (int m = 0; m < 4; ++m)
; #pragma unroll
;                 for (int n = 0; n < 2; ++n) acc[a][b][m][n] = (f32x4){0.f, 0.f, 0.f, 0.f};
;     bf16x8 At[4][2], B0[2][2], B1[2][2];
;     const char* cA = (const char*)g.A + (size_t)cur.pm * tstep; const char* cB = (const char*)g.Bt + (size_t)cur.pn * tstep;
;     S.a_ready(cur);
;     if constexpr (SP2) {
;         PG8_STAGE(PG8_SB(0, 0), cB, voffB); PG8_STAGE(PG8_SB(0, 1), cB + hstep, voffB); PG8_STAGE(PG8_SA(0, 0), cA, voffA); PG8_STAGE(PG8_SA(0, 1), cA + hstep, voffA);
;         if (wr == 1) PG8_BAR;
;         PG8_WAIT_V(2); PG8_BAR;
;         PG8_STAGE(PG8_SB(1, 0), cB + kstep, voffB); PG8_STAGE(PG8_SA(1, 0), cA + kstep, voffA); PG8_STAGE(PG8_SB(1, 1), cB + hstep + kstep, voffB);
;         PG8_WAIT_V(6); PG8_BAR;
.LBB0_114:
	s_and_b32 s47, s4, 3
	s_lshl_b32 s4, s5, 13
	s_lshl_b32 s19, s47, 12
	s_add_u32 s14, s10, 0x8a00000
	s_mov_b64 s[16:17], 0x80
	s_addc_u32 s15, s11, 0
	s_add_i32 m0, s31, 0x18000
	v_lshl_add_u64 v[6:7], v[6:7], 0, s[16:17]
	s_waitcnt vmcnt(2)
	s_barrier
	global_load_lds_dwordx4 v[6:7], off
	v_lshl_add_u64 v[4:5], v[4:5], 0, s[16:17]
	s_add_i32 m0, s31, 0x1a000
	s_add_i32 s48, s31, 0x8000
	s_add_i32 s49, s31, 0xa000
	global_load_lds_dwordx4 v[4:5], off
	v_lshl_add_u64 v[0:1], v[0:1], 0, s[16:17]
	s_mov_b32 m0, s48
	s_add_u32 s22, s26, 0x40080
	global_load_lds_dwordx4 v[0:1], off
	v_lshl_add_u64 v[0:1], v[2:3], 0, s[16:17]
	s_mov_b32 m0, s49
	s_addc_u32 s23, s27, 0
	global_load_lds_dwordx4 v[0:1], off
	s_add_i32 m0, s31, 0x1c000
	v_lshl_add_u64 v[0:1], s[22:23], 0, v[130:131]
	global_load_lds_dwordx4 v[0:1], off
	v_lshl_add_u64 v[0:1], s[22:23], 0, v[134:135]
	s_add_i32 m0, s31, 0x1e000
	v_bfe_u32 v2, v8, 4, 2
	global_load_lds_dwordx4 v[0:1], off
	v_and_b32_e32 v1, 15, v8
	v_lshlrev_b32_e32 v0, 4, v2
	v_lshlrev_b32_e32 v4, 2, v8
	v_lshl_or_b32 v192, s5, 6, v1
	v_lshl_add_u32 v239, v192, 6, v0
	v_add_u32_e32 v239, 0x20080, v239
	v_and_b32_e32 v238, 63, v8
	v_lshlrev_b32_e32 v238, 4, v238
	v_and_b32_e32 v240, 0xffffffc0, v8
	v_lshl_add_u32 v238, v240, 5, v238
	v_lshl_or_b32 v1, v1, 6, v0
	v_and_b32_e32 v4, 32, v4
	v_bitop3_b32 v5, v1, s4, v4 bitop3:0xde
	v_bitop3_b32 v193, v1, s19, v4 bitop3:0xde
	v_mov_b32_e32 v1, v131
	v_lshl_add_u64 v[0:1], s[10:11], 0, v[0:1]
	s_add_u32 s100, s10, 0x8900000
	s_addc_u32 s101, s11, 0
	s_mov_b64 s[4:5], 0x8900000
	v_lshl_add_u64 v[136:137], v[0:1], 0, s[4:5]
	v_lshlrev_b32_e32 v0, 5, v2
	v_mov_b32_e32 v1, v131
	v_add_u32_e32 v138, 0x24080, v0
	v_and_b32_e32 v139, 63, v8
	v_lshlrev_b32_e32 v139, 4, v139
	s_mov_b64 exec, 0xffff
	s_mov_b32 m0, 0x24080
	s_nop 0
	global_load_lds_dwordx4 v139, s[8:9]
	s_mov_b64 exec, -1
	v_lshlrev_b32_e32 v0, 14, v12
	v_and_b32_e32 v0, 0xffff8000, v0
	v_lshl_add_u32 v0, v13, 11, v0
	v_and_b32_e32 v1, 1, v12
	v_lshl_or_b32 v0, v1, 6, v0
	v_lshl_add_u32 v140, v14, 1, v0
	v_lshlrev_b32_e32 v0, 14, v9
	v_and_b32_e32 v0, 0xffff8000, v0
	s_waitcnt vmcnt(6)
	s_cmpk_lt_u32 s18, 0x100
	v_lshl_add_u32 v0, v10, 11, v0
	v_and_b32_e32 v1, 1, v9
	v_lshlrev_b32_e32 v3, 3, v2
	s_cselect_b64 s[18:19], -1, 0
	v_lshl_or_b32 v0, v1, 6, v0
	s_add_i32 s54, 0, 0x10000
	s_add_i32 s55, 0, 0x14000
	v_or_b32_e32 v194, 16, v192
	v_or_b32_e32 v195, 32, v192
	v_or_b32_e32 v196, 48, v192
	s_ashr_i32 s50, s28, 31
	s_mov_b32 s51, s28
	s_ashr_i32 s52, s2, 31
	v_lshl_or_b32 v197, s47, 6, v3
	v_mov_b32_e32 v141, v131
	v_lshl_add_u32 v142, v11, 1, v0
	v_mov_b32_e32 v143, v131
	v_mov_b64_e32 v[144:145], 0x280
	v_mov_b64_e32 v[146:147], 0x27f
	s_movk_i32 s53, 0x51
	v_add_u32_e32 v198, s54, v193
	v_add_u32_e32 v199, s55, v193
	v_add_u32_e32 v200, 0, v5
	v_mov_b32_e32 v202, 0x358637bd
	s_movk_i32 s56, 0x1400
	v_mov_b32_e32 v203, 0x3e38aa3b
	v_mov_b32_e32 v204, 0x3e000000
	s_barrier
	s_branch .LBB0_117

; __device__ __forceinline__ float row_part(const float* ss, int row, int fq) { const f32x4 a = ((const f32x4*)(ss + (size_t)row * 16))[fq]; return (a[0] + a[1]) + (a[2] + a[3]); }
; __device__ __forceinline__ float row_finish(float t) { t += shx(t, 16); t += shx(t, 32); return __builtin_amdgcn_rsqf(t * (1.0f / 1024.0f) + RMS_EPS); }
;     __device__ __forceinline__ void operator()(const f32x4 (&acc)[2][2][4][2], const Unit& u, int wr, int wc, int fr, int fq) const {
;         const int g = u.pn * 4 + wc;
;         int mode = 0; const float* w = mqw; float sc = 1.f, nsc = 1.f;
;         if (g >= 36) { mode = 2; w = mqw; nsc = qscale; }
;         else if (diff) { if (g < 12) { mode = 2; w = qw; nsc = qscale; } else if (g < 24) { mode = 2; w = kw; } }
;         else { if (g >= 6 && g < 12) sc = 0.125f; else if (g >= 24) mode = 1; }
;         f32x4 wv[2][2];
; #pragma unroll
;         for (int bj = 0; bj < 2; ++bj)
; #pragma unroll
;             for (int n = 0; n < 2; ++n) wv[bj][n] = *(const f32x4*)(w + 32 * bj + 8 * fq + 4 * n) * nsc;
;         const int lcol = u.pn * 256 + 64 * wc + 8 * fq;
;         float rs[2][4];
; #pragma unroll
;         for (int ai = 0; ai < 2; ++ai)
; #pragma unroll
;             for (int m = 0; m < 4; ++m) rs[ai][m] = row_part(ss, u.pm * BM + ai * HALF + wr * 64 + m * 16 + fr, fq);
; #pragma unroll
;         for (int ai = 0; ai < 2; ++ai)
; #pragma unroll
;             for (int m = 0; m < 4; ++m) rs[ai][m] = row_finish(rs[ai][m]);
.LBB0_123:
	s_lshl_b32 s9, s36, 2
	s_or_b32 s11, s9, s47
	s_cmp_gt_i32 s11, 35
	s_cselect_b64 s[34:35], -1, 0
	s_cmp_lt_i32 s11, 36
	s_cselect_b64 s[42:43], -1, 0
	s_add_i32 s11, s11, -12
	s_cmp_lt_u32 s11, -6
	s_cselect_b64 s[40:41], -1, 0
	s_sub_i32 s9, s9, 24
	s_cmp_gt_u32 s9, 11
	s_cselect_b64 s[26:27], -1, 0
	s_lshl_b32 s9, s38, 8
	v_add_u32_e32 v176, s9, v192
	v_ashrrev_i32_e32 v177, 31, v176
	v_or_b32_e32 v158, 16, v176
	v_lshlrev_b64 v[148:149], 6, v[176:177]
	v_ashrrev_i32_e32 v159, 31, v158
	v_lshl_add_u64 v[148:149], v[136:137], 0, v[148:149]
	v_lshlrev_b64 v[158:159], 6, v[158:159]
	ds_read_b128 v[150:153], v138 offset:16
	ds_read_b128 v[154:157], v138
	ds_read_b128 v[168:171], v138 offset:144
	ds_read_b128 v[178:181], v138 offset:128
	v_lshl_add_u64 v[158:159], v[136:137], 0, v[158:159]
	ds_read_b128 v[182:185], v239
	ds_read_b128 v[186:189], v239 offset:1024
	v_or_b32_e32 v148, 32, v176
	v_ashrrev_i32_e32 v149, 31, v148
	v_or_b32_e32 v158, 48, v176
	v_lshlrev_b64 v[148:149], 6, v[148:149]
	v_ashrrev_i32_e32 v159, 31, v158
	v_lshl_add_u64 v[148:149], v[136:137], 0, v[148:149]
	v_lshlrev_b64 v[158:159], 6, v[158:159]
	v_lshl_add_u64 v[158:159], v[136:137], 0, v[158:159]
	ds_read_b128 v[206:209], v239 offset:2048
	ds_read_b128 v[210:213], v239 offset:3072
	v_add_u32_e32 v174, 0x80, v176
	v_ashrrev_i32_e32 v175, 31, v174
	v_add_u32_e32 v172, 0x90, v176
	v_lshlrev_b64 v[148:149], 6, v[174:175]
	v_ashrrev_i32_e32 v173, 31, v172
	v_lshl_add_u64 v[148:149], v[136:137], 0, v[148:149]
	v_lshlrev_b64 v[158:159], 6, v[172:173]
	v_lshl_add_u64 v[158:159], v[136:137], 0, v[158:159]
	ds_read_b128 v[214:217], v239 offset:8192
	ds_read_b128 v[218:221], v239 offset:9216
	v_add_u32_e32 v166, 0xa0, v176
	v_ashrrev_i32_e32 v167, 31, v166
	v_lshlrev_b64 v[148:149], 6, v[166:167]
	v_lshl_add_u64 v[148:149], v[136:137], 0, v[148:149]
	ds_read_b128 v[222:225], v239 offset:10240
	v_add_u32_e32 v148, 0xb0, v176
	v_ashrrev_i32_e32 v149, 31, v148
	v_lshlrev_b64 v[158:159], 6, v[148:149]
	v_lshl_add_u64 v[158:159], v[136:137], 0, v[158:159]
	ds_read_b128 v[226:229], v239 offset:11264
	v_mov_b32_e32 v149, v201
	v_mov_b32_e32 v158, v201
	v_cndmask_b32_e64 v190, v203, 1.0, s[42:43]
	v_lshlrev_b32_e32 v158, 2, v158
	v_xor_b32_e32 v173, 0x80, v158
	v_lshlrev_b32_e32 v149, 2, v149
	v_xor_b32_e32 v149, 64, v149
	v_mov_b32_e32 v167, v201
	s_mov_b64 s[38:39], -1
	v_lshlrev_b32_e32 v167, 2, v167
	v_xor_b32_e32 v167, 64, v167
	s_and_b64 vcc, exec, s[42:43]
	s_waitcnt lgkmcnt(0)
	v_pk_mul_f32 v[158:159], v[190:191], v[152:153] op_sel_hi:[0,1]
	v_pk_mul_f32 v[160:161], v[190:191], v[150:151] op_sel_hi:[0,1]
	v_pk_mul_f32 v[152:153], v[190:191], v[168:169] op_sel_hi:[0,1]
	v_pk_mul_f32 v[150:151], v[190:191], v[170:171] op_sel_hi:[0,1]
	v_mov_b32_e32 v168, v183
	v_mov_b32_e32 v169, v184
	v_mov_b32_e32 v183, v185
	v_pk_add_f32 v[168:169], v[168:169], v[182:183]
	v_add_f32_e32 v170, v186, v187
	v_add_f32_e32 v168, v168, v169
	v_mov_b32_e32 v149, v168
	s_nop 1
	v_permlane16_swap_b32_e32 v149, v168
	v_add_f32_e32 v171, v188, v189
	v_add_f32_e32 v169, v170, v171
	v_mov_b32_e32 v167, v169
	s_nop 1
	v_permlane16_swap_b32_e32 v167, v169
	v_pk_mul_f32 v[162:163], v[190:191], v[156:157] op_sel_hi:[0,1]
	s_waitcnt lgkmcnt(0)
	v_add_f32_e32 v149, v168, v149
	v_mov_b32_e32 v168, v149
	s_nop 1
	v_permlane32_swap_b32_e32 v168, v149
	v_pk_mul_f32 v[156:157], v[190:191], v[178:179] op_sel_hi:[0,1]
	v_add_f32_e32 v179, v212, v213
	s_waitcnt lgkmcnt(0)
	v_add_f32_e32 v212, v169, v167
	v_add_f32_e32 v175, v206, v207
	s_waitcnt lgkmcnt(0)
	v_add_f32_e32 v149, v149, v168
	v_fmamk_f32 v149, v149, 0x3a800000, v202
	v_rsq_f32_e32 v168, v149
	v_mov_b32_e32 v149, v201
	v_add_f32_e32 v177, v208, v209
	v_lshlrev_b32_e32 v149, 2, v149
	v_xor_b32_e32 v149, 0x80, v149
	v_mov_b32_e32 v213, v212
	s_nop 1
	v_permlane32_swap_b32_e32 v213, v212
	v_mov_b32_e32 v149, v201
	v_add_f32_e32 v170, v175, v177
	v_lshlrev_b32_e32 v149, 2, v149
	v_xor_b32_e32 v149, 64, v149
	v_mov_b32_e32 v149, v170
	s_nop 1
	v_permlane16_swap_b32_e32 v149, v170
	v_mov_b32_e32 v167, v201
	v_mov_b32_e32 v169, v201
	v_add_f32_e32 v178, v210, v211
	v_lshlrev_b32_e32 v169, 2, v169
	v_add_f32_e32 v171, v178, v179
	v_xor_b32_e32 v169, 64, v169
	v_mov_b32_e32 v169, v171
	s_nop 1
	v_permlane16_swap_b32_e32 v169, v171
	s_waitcnt lgkmcnt(0)
	v_add_f32_e32 v210, v170, v149
	v_lshlrev_b32_e32 v149, 2, v167
	v_xor_b32_e32 v149, 0x80, v149
	v_mov_b32_e32 v211, v210
	s_nop 1
	v_permlane32_swap_b32_e32 v211, v210
	v_mov_b32_e32 v149, v201
	s_waitcnt lgkmcnt(0)
; __device__ __forceinline__ float row_part(const float* ss, int row, int fq) { const f32x4 a = ((const f32x4*)(ss + (size_t)row * 16))[fq]; return (a[0] + a[1]) + (a[2] + a[3]); }
; __device__ __forceinline__ float row_finish(float t) { t += shx(t, 16); t += shx(t, 32); return __builtin_amdgcn_rsqf(t * (1.0f / 1024.0f) + RMS_EPS); }
; __device__ __forceinline__ float sq4(f32x4 v) { return (v[0] * v[0] + v[1] * v[1]) + (v[2] * v[2] + v[3] * v[3]); }
;     __device__ __forceinline__ void operator()(const f32x4 (&acc)[2][2][4][2], const Unit& u, int wr, int wc, int fr, int fq) const {
;     ...
;             for (int m = 0; m < 4; ++m) rs[ai][m] = row_part(ss, u.pm * BM + ai * HALF + wr * 64 + m * 16 + fr, fq);
; #pragma unroll
;         for (int ai = 0; ai < 2; ++ai)
; #pragma unroll
;             for (int m = 0; m < 4; ++m) rs[ai][m] = row_finish(rs[ai][m]);
; #pragma unroll
;         for (int ai = 0; ai < 2; ++ai)
; #pragma unroll
;             for (int m = 0; m < 4; ++m) {
;                 const int row = u.pm * BM + ai * HALF + wr * 64 + m * 16 + fr;
;                 const float rstd = rs[ai][m];
;                 f32x4 v[2][2];
; #pragma unroll
;                 for (int bj = 0; bj < 2; ++bj)
; #pragma unroll
;                     for (int n = 0; n < 2; ++n) v[bj][n] = acc[ai][bj][m][n] * rstd;
;                 if (mode == 2) {
;                     float q = (sq4(v[0][0]) + sq4(v[0][1])) + (sq4(v[1][0]) + sq4(v[1][1]));
;                     q += shx(q, 16); q += shx(q, 32);
;                     const float r2 = __builtin_amdgcn_rsqf(q * (1.0f / 64.0f) + RMS_EPS);
; #pragma unroll
;                     for (int bj = 0; bj < 2; ++bj)
; #pragma unroll
;                         for (int n = 0; n < 2; ++n) v[bj][n] = v[bj][n] * r2 * wv[bj][n];
	v_add_f32_e32 v208, v171, v169
	v_lshlrev_b32_e32 v149, 2, v149
	v_xor_b32_e32 v149, 0x80, v149
	v_mov_b32_e32 v209, v208
	s_nop 1
	v_permlane32_swap_b32_e32 v209, v208
	v_mov_b32_e32 v149, v201
	v_pk_mul_f32 v[164:165], v[190:191], v[154:155] op_sel_hi:[0,1]
	v_pk_mul_f32 v[154:155], v[190:191], v[180:181] op_sel_hi:[0,1]
	v_add_f32_e32 v180, v214, v215
	v_add_f32_e32 v181, v216, v217
	v_lshlrev_b32_e32 v149, 2, v149
	v_add_f32_e32 v175, v180, v181
	v_xor_b32_e32 v149, 64, v149
	v_mov_b32_e32 v149, v175
	s_nop 1
	v_permlane16_swap_b32_e32 v149, v175
	v_mov_b32_e32 v167, v201
	v_mov_b32_e32 v169, v201
	v_add_f32_e32 v182, v218, v219
	v_add_f32_e32 v183, v220, v221
	v_lshlrev_b32_e32 v169, 2, v169
	v_add_f32_e32 v177, v182, v183
	v_xor_b32_e32 v169, 64, v169
	v_mov_b32_e32 v169, v177
	s_nop 1
	v_permlane16_swap_b32_e32 v169, v177
	s_waitcnt lgkmcnt(0)
	v_add_f32_e32 v206, v175, v149
	v_lshlrev_b32_e32 v149, 2, v167
	v_xor_b32_e32 v149, 0x80, v149
	v_mov_b32_e32 v207, v206
	s_nop 1
	v_permlane32_swap_b32_e32 v207, v206
	v_mov_b32_e32 v149, v201
	s_waitcnt lgkmcnt(0)
	v_add_f32_e32 v177, v177, v169
	v_lshlrev_b32_e32 v149, 2, v149
	v_xor_b32_e32 v149, 0x80, v149
	v_mov_b32_e32 v205, v177
	s_nop 1
	v_permlane32_swap_b32_e32 v205, v177
	v_mov_b32_e32 v149, v201
	v_add_f32_e32 v184, v222, v223
	v_add_f32_e32 v185, v224, v225
	v_lshlrev_b32_e32 v149, 2, v149
	v_add_f32_e32 v178, v184, v185
	v_xor_b32_e32 v149, 64, v149
	v_mov_b32_e32 v167, v201
	v_mov_b32_e32 v169, v201
	v_mov_b32_e32 v149, v178
	s_nop 1
	v_permlane16_swap_b32_e32 v149, v178
	v_add_f32_e32 v186, v226, v227
	v_add_f32_e32 v187, v228, v229
	v_lshlrev_b32_e32 v169, 2, v169
	v_add_f32_e32 v179, v186, v187
	v_xor_b32_e32 v169, 64, v169
	v_mov_b32_e32 v169, v179
	s_nop 1
	v_permlane16_swap_b32_e32 v169, v179
	s_waitcnt lgkmcnt(0)
	v_add_f32_e32 v173, v178, v149
	v_lshlrev_b32_e32 v149, 2, v167
	v_mov_b32_e32 v167, v201
	v_xor_b32_e32 v149, 0x80, v149
	v_lshlrev_b32_e32 v167, 2, v167
	v_mov_b32_e32 v175, v173
	s_nop 1
	v_permlane32_swap_b32_e32 v175, v173
	s_waitcnt lgkmcnt(0)
	v_add_f32_e32 v149, v179, v169
	v_xor_b32_e32 v167, 0x80, v167
	v_mov_b32_e32 v167, v149
	s_nop 1
	v_permlane32_swap_b32_e32 v167, v149
	v_pk_mul_f32 v[190:191], v[126:127], v[168:169] op_sel_hi:[1,0]
	v_pk_mul_f32 v[184:185], v[124:125], v[168:169] op_sel_hi:[1,0]
	v_pk_mul_f32 v[186:187], v[122:123], v[168:169] op_sel_hi:[1,0]
	v_pk_mul_f32 v[188:189], v[120:121], v[168:169] op_sel_hi:[1,0]
	v_pk_mul_f32 v[180:181], v[118:119], v[168:169] op_sel_hi:[1,0]
	v_pk_mul_f32 v[182:183], v[116:117], v[168:169] op_sel_hi:[1,0]
	v_pk_mul_f32 v[178:179], v[114:115], v[168:169] op_sel_hi:[1,0]
	v_pk_mul_f32 v[170:171], v[112:113], v[168:169] op_sel_hi:[1,0]
	s_cbranch_vccnz .LBB0_125
	v_mov_b32_e32 v114, v185
	v_mov_b32_e32 v115, v183
	v_mov_b32_e32 v112, v184
	v_mov_b32_e32 v113, v182
	v_pk_mul_f32 v[114:115], v[114:115], v[114:115]
	v_mov_b32_e32 v116, v191
	v_mov_b32_e32 v117, v181
	v_pk_fma_f32 v[112:113], v[112:113], v[112:113], v[114:115]
	v_mov_b32_e32 v114, v190
	v_mov_b32_e32 v115, v180
	v_pk_mul_f32 v[116:117], v[116:117], v[116:117]
	v_mov_b32_e32 v118, v187
	v_pk_fma_f32 v[114:115], v[114:115], v[114:115], v[116:117]
	v_mov_b32_e32 v116, v189
	v_mov_b32_e32 v117, v171
	v_pk_add_f32 v[112:113], v[112:113], v[114:115]
	v_mov_b32_e32 v114, v188
	v_mov_b32_e32 v115, v170
	v_pk_mul_f32 v[116:117], v[116:117], v[116:117]
	v_mov_b32_e32 v119, v179
	v_pk_fma_f32 v[114:115], v[114:115], v[114:115], v[116:117]
	v_mov_b32_e32 v116, v186
	v_mov_b32_e32 v117, v178
	v_pk_mul_f32 v[118:119], v[118:119], v[118:119]
	s_mov_b64 s[38:39], 0
	v_pk_fma_f32 v[116:117], v[116:117], v[116:117], v[118:119]
	s_nop 0
	v_pk_add_f32 v[114:115], v[114:115], v[116:117]
	s_nop 0
	v_pk_add_f32 v[112:113], v[112:113], v[114:115]
	s_nop 0
	v_add_f32_e32 v112, v112, v113
	v_mov_b32_e32 v113, v201
	s_nop 0
	v_lshlrev_b32_e32 v113, 2, v113
	v_xor_b32_e32 v113, 64, v113
	v_mov_b32_e32 v113, v112
	s_nop 1
	v_permlane16_swap_b32_e32 v113, v112
	s_waitcnt lgkmcnt(0)
	v_add_f32_e32 v112, v112, v113
	v_mov_b32_e32 v113, v201
	s_nop 0
	v_lshlrev_b32_e32 v113, 2, v113
	v_xor_b32_e32 v113, 0x80, v113
	v_mov_b32_e32 v113, v112
	s_nop 1
	v_permlane32_swap_b32_e32 v113, v112
	s_waitcnt lgkmcnt(0)
	v_add_f32_e32 v112, v112, v113
	v_fmamk_f32 v112, v112, 0x3c800000, v202
	v_rsq_f32_e32 v124, v112
	s_nop 0
	v_pk_mul_f32 v[112:113], v[184:185], v[124:125] op_sel_hi:[1,0]
	v_pk_mul_f32 v[114:115], v[190:191], v[124:125] op_sel_hi:[1,0]
	v_pk_mul_f32 v[116:117], v[188:189], v[124:125] op_sel_hi:[1,0]
	v_pk_mul_f32 v[118:119], v[186:187], v[124:125] op_sel_hi:[1,0]
	v_pk_mul_f32 v[120:121], v[182:183], v[124:125] op_sel_hi:[1,0]
	v_pk_mul_f32 v[122:123], v[180:181], v[124:125] op_sel_hi:[1,0]
	v_pk_mul_f32 v[168:169], v[170:171], v[124:125] op_sel_hi:[1,0]
	v_pk_mul_f32 v[124:125], v[178:179], v[124:125] op_sel_hi:[1,0]
	v_pk_mul_f32 v[114:115], v[162:163], v[114:115]
	v_pk_mul_f32 v[112:113], v[164:165], v[112:113]
	v_pk_mul_f32 v[118:119], v[158:159], v[118:119]
	v_pk_mul_f32 v[116:117], v[160:161], v[116:117]
	v_pk_mul_f32 v[122:123], v[154:155], v[122:123]
	v_pk_mul_f32 v[120:121], v[156:157], v[120:121]
	v_pk_mul_f32 v[126:127], v[150:151], v[124:125]
	v_pk_mul_f32 v[124:125], v[152:153], v[168:169]

;     __device__ bool next(int i, Unit& u) const { if (i > 0) return false; const int t = c - first; if (t < 0 || t >= nM * nN) return false; u.pm = t % nM; u.pn = t / nM; return true; }
; #define PG8_STAGE(bufoff, gbase, voff) do { _Pragma("unroll") for (int _i = 0; _i < 2; ++_i) \
;         __builtin_amdgcn_global_load_lds((const unsigned*)((const char*)(gbase) + (voff)[_i]), (PG8_LAS unsigned*)(lds + (bufoff) + ldsw + _i * 8192), 16, 0, 0); } while (0)
; #define PG8_WAIT_V(n) asm volatile("s_waitcnt vmcnt(" #n ")" ::: "memory")
; #define PG8_BAR __builtin_amdgcn_s_barrier()
;     __device__ __forceinline__ void operator()(const f32x4 (&acc)[2][2][4][2], const Unit& u, int wr, int wc, int fr, int fq) const {
;     ...
;             for (int n = 0; n < 2; ++n) wv[bj][n] = *(const f32x4*)(w + 32 * bj + 8 * fq + 4 * n) * nsc;
; template <class Epi, class Sched, bool ALIGN_EPI = false, bool SP2 = false>
; __device__ __forceinline__ void gemm_phase(PG8_LAS unsigned char* lds, const Gemm g, const Sched& S, const Epi& E, int tid_in) {
;     ...
;     const int aoff = lds_byte(wr * 64 + fr, fq * 8), boff = lds_byte(wc * 32 + fr, fq * 8);
;     ...
;     Unit cur, nxt; int ui = 0;
;     if (!S.next(0, cur)) return;
;     f32x4 acc[2][2][4][2];
; #pragma unroll
;     for (int a = 0; a < 2; ++a)
; #pragma unroll
;         for (int b = 0; b < 2; ++b)
; #pragma unroll
;             for (int m = 0; m < 4; ++m)
; #pragma unroll
;                 for (int n = 0; n < 2; ++n) acc[a][b][m][n] = (f32x4){0.f, 0.f, 0.f, 0.f};
;     bf16x8 At[4][2], B0[2][2], B1[2][2];
;     const char* cA = (const char*)g.A + (size_t)cur.pm * tstep; const char* cB = (const char*)g.Bt + (size_t)cur.pn * tstep;
;     S.a_ready(cur);
;     if constexpr (SP2) {
;         PG8_STAGE(PG8_SB(0, 0), cB, voffB); PG8_STAGE(PG8_SB(0, 1), cB + hstep, voffB); PG8_STAGE(PG8_SA(0, 0), cA, voffA); PG8_STAGE(PG8_SA(0, 1), cA + hstep, voffA);
;         if (wr == 1) PG8_BAR;
;         PG8_WAIT_V(2); PG8_BAR;
;         PG8_STAGE(PG8_SB(1, 0), cB + kstep, voffB); PG8_STAGE(PG8_SA(1, 0), cA + kstep, voffA); PG8_STAGE(PG8_SB(1, 1), cB + hstep + kstep, voffB);
;         PG8_WAIT_V(6); PG8_BAR;
.LBB0_1182:
	s_and_b32 s67, s12, 3
	s_lshl_b32 s4, s13, 13
	s_lshl_b32 s5, s67, 12
	s_add_u32 s18, s26, 0x8a00000
	s_mov_b64 s[20:21], 0x80
	s_addc_u32 s19, s27, 0
	s_add_i32 m0, s62, 0x18000
	v_lshl_add_u64 v[6:7], v[6:7], 0, s[20:21]
	s_waitcnt vmcnt(2)
	s_barrier
	global_load_lds_dwordx4 v[6:7], off
	v_lshl_add_u64 v[4:5], v[4:5], 0, s[20:21]
	s_add_i32 m0, s62, 0x1a000
	s_add_i32 s68, s62, 0x8000
	s_add_i32 s69, s62, 0xa000
	global_load_lds_dwordx4 v[4:5], off
	v_lshl_add_u64 v[0:1], v[0:1], 0, s[20:21]
	s_mov_b32 m0, s68
	s_add_u32 s14, s46, 0x40080
	global_load_lds_dwordx4 v[0:1], off
	v_lshl_add_u64 v[0:1], v[2:3], 0, s[20:21]
	s_mov_b32 m0, s69
	s_addc_u32 s15, s47, 0
	global_load_lds_dwordx4 v[0:1], off
	s_add_i32 m0, s62, 0x1c000
	v_lshl_add_u64 v[0:1], s[14:15], 0, v[130:131]
	global_load_lds_dwordx4 v[0:1], off
	v_lshl_add_u64 v[0:1], s[14:15], 0, v[134:135]
	s_add_i32 m0, s62, 0x1e000
	v_bfe_u32 v2, v8, 4, 2
	global_load_lds_dwordx4 v[0:1], off
	v_and_b32_e32 v1, 15, v8
	v_lshlrev_b32_e32 v0, 4, v2
	v_lshlrev_b32_e32 v4, 2, v8
	v_lshl_or_b32 v192, s13, 6, v1
	v_lshl_add_u32 v239, v192, 6, v0
	v_add_u32_e32 v239, 0x20080, v239
	v_and_b32_e32 v238, 63, v8
	v_lshlrev_b32_e32 v238, 4, v238
	v_and_b32_e32 v240, 0xffffffc0, v8
	v_lshl_add_u32 v238, v240, 5, v238
	v_lshl_or_b32 v1, v1, 6, v0
	v_and_b32_e32 v4, 32, v4
	v_bitop3_b32 v5, v1, s4, v4 bitop3:0xde
	v_bitop3_b32 v193, v1, s5, v4 bitop3:0xde
	v_mov_b32_e32 v1, v131
	v_lshl_add_u64 v[0:1], s[26:27], 0, v[0:1]
	s_add_u32 s100, s26, 0x8900000
	s_addc_u32 s101, s27, 0
	s_mov_b64 s[12:13], 0x8900000
	v_lshl_add_u64 v[136:137], v[0:1], 0, s[12:13]
	v_lshlrev_b32_e32 v0, 5, v2
	v_mov_b32_e32 v1, v131
	v_add_u32_e32 v138, 0x24080, v0
	v_and_b32_e32 v139, 63, v8
	v_lshlrev_b32_e32 v139, 4, v139
	s_mov_b64 exec, 0xffff
	s_mov_b32 m0, 0x23e80
	s_nop 0
	global_load_lds_dwordx4 v139, s[24:25] offset:512
	s_mov_b64 exec, -1
	v_lshlrev_b32_e32 v0, 14, v12
	v_and_b32_e32 v0, 0xffff8000, v0
	v_lshl_add_u32 v0, v13, 11, v0
	v_and_b32_e32 v1, 1, v12
	v_lshl_or_b32 v0, v1, 6, v0
	v_lshl_add_u32 v140, v14, 1, v0
	v_lshlrev_b32_e32 v0, 14, v9
	v_and_b32_e32 v0, 0xffff8000, v0
	s_waitcnt vmcnt(6)
	s_cmpk_lt_u32 s0, 0x100
	v_lshl_add_u32 v0, v10, 11, v0
	v_and_b32_e32 v1, 1, v9
	v_lshlrev_b32_e32 v3, 3, v2
	s_cselect_b64 s[22:23], -1, 0
	v_lshl_or_b32 v0, v1, 6, v0
	s_add_i32 s73, 0, 0x10000
	s_add_i32 s40, 0, 0x14000
	v_or_b32_e32 v194, 16, v192
	v_or_b32_e32 v195, 32, v192
	v_or_b32_e32 v196, 48, v192
	s_ashr_i32 s70, s28, 31
	s_mov_b32 s71, s28
	s_ashr_i32 s72, s2, 31
	v_lshl_or_b32 v197, s67, 6, v3
	v_mov_b32_e32 v141, v131
	v_lshl_add_u32 v142, v11, 1, v0
	v_mov_b32_e32 v143, v131
	v_mov_b64_e32 v[144:145], 0x280
	v_mov_b64_e32 v[146:147], 0x27f
	v_add_u32_e32 v198, s73, v193
	v_add_u32_e32 v199, s40, v193
	v_add_u32_e32 v200, 0, v5
	v_mov_b32_e32 v202, 0x358637bd
	s_movk_i32 s12, 0x1400
	v_mov_b32_e32 v203, 0x3e38aa3b
	v_mov_b32_e32 v204, 0x3e000000
	s_barrier
	s_branch .LBB0_1185

; __device__ __forceinline__ float row_part(const float* ss, int row, int fq) { const f32x4 a = ((const f32x4*)(ss + (size_t)row * 16))[fq]; return (a[0] + a[1]) + (a[2] + a[3]); }
; __device__ __forceinline__ float row_finish(float t) { t += shx(t, 16); t += shx(t, 32); return __builtin_amdgcn_rsqf(t * (1.0f / 1024.0f) + RMS_EPS); }
;     __device__ __forceinline__ void operator()(const f32x4 (&acc)[2][2][4][2], const Unit& u, int wr, int wc, int fr, int fq) const {
;         const int g = u.pn * 4 + wc;
;         int mode = 0; const float* w = mqw; float sc = 1.f, nsc = 1.f;
;         if (g >= 36) { mode = 2; w = mqw; nsc = qscale; }
;         else if (diff) { if (g < 12) { mode = 2; w = qw; nsc = qscale; } else if (g < 24) { mode = 2; w = kw; } }
;         else { if (g >= 6 && g < 12) sc = 0.125f; else if (g >= 24) mode = 1; }
;         f32x4 wv[2][2];
; #pragma unroll
;         for (int bj = 0; bj < 2; ++bj)
; #pragma unroll
;             for (int n = 0; n < 2; ++n) wv[bj][n] = *(const f32x4*)(w + 32 * bj + 8 * fq + 4 * n) * nsc;
;         const int lcol = u.pn * 256 + 64 * wc + 8 * fq;
;         float rs[2][4];
; #pragma unroll
;         for (int ai = 0; ai < 2; ++ai)
; #pragma unroll
;             for (int m = 0; m < 4; ++m) rs[ai][m] = row_part(ss, u.pm * BM + ai * HALF + wr * 64 + m * 16 + fr, fq);
; #pragma unroll
;         for (int ai = 0; ai < 2; ++ai)
; #pragma unroll
;             for (int m = 0; m < 4; ++m) rs[ai][m] = row_finish(rs[ai][m]);
.LBB0_1191:
	ds_read_b128 v[148:151], v138 offset:16
	ds_read_b128 v[152:155], v138
	ds_read_b128 v[166:169], v138 offset:144
	ds_read_b128 v[170:173], v138 offset:128
	s_lshl_b32 s0, s50, 2
	s_or_b32 s4, s0, s67
	s_cmp_gt_i32 s4, 35
	s_cselect_b64 s[48:49], -1, 0
	s_cmp_lt_i32 s4, 36
	s_cselect_b64 s[56:57], -1, 0
	s_add_i32 s4, s4, -12
	s_cmp_lt_u32 s4, -6
	s_cselect_b64 s[54:55], -1, 0
	s_sub_i32 s0, s0, 24
	s_cmp_gt_u32 s0, 11
	s_cselect_b64 s[46:47], -1, 0
	s_lshl_b32 s0, s52, 8
	v_add_u32_e32 v176, s0, v192
	v_cndmask_b32_e64 v158, v203, 1.0, s[56:57]
	v_ashrrev_i32_e32 v177, 31, v176
	v_add_u32_e32 v174, 0x80, v176
	v_ashrrev_i32_e32 v175, 31, v174
	s_mov_b64 s[52:53], -1
	s_and_b64 vcc, exec, s[56:57]
	s_waitcnt lgkmcnt(0)
	v_pk_mul_f32 v[150:151], v[158:159], v[150:151] op_sel_hi:[0,1]
	v_pk_mul_f32 v[160:161], v[158:159], v[152:153] op_sel_hi:[0,1]
	v_pk_mul_f32 v[152:153], v[158:159], v[148:149] op_sel_hi:[0,1]
	v_lshlrev_b64 v[148:149], 6, v[176:177]
	v_lshl_add_u64 v[148:149], v[136:137], 0, v[148:149]
	v_pk_mul_f32 v[156:157], v[158:159], v[154:155] op_sel_hi:[0,1]
	v_pk_mul_f32 v[162:163], v[158:159], v[172:173] op_sel_hi:[0,1]
	v_pk_mul_f32 v[164:165], v[158:159], v[170:171] op_sel_hi:[0,1]
	v_pk_mul_f32 v[154:155], v[158:159], v[168:169] op_sel_hi:[0,1]
	v_pk_mul_f32 v[158:159], v[158:159], v[166:167] op_sel_hi:[0,1]
	ds_read_b128 v[166:169], v239
	v_add_u32_e32 v172, 0x90, v176
	v_ashrrev_i32_e32 v173, 31, v172
	s_waitcnt lgkmcnt(0)
	v_mov_b32_e32 v148, v167
	v_mov_b32_e32 v149, v168
	v_mov_b32_e32 v167, v169
	v_pk_add_f32 v[148:149], v[148:149], v[166:167]
	s_nop 0
	v_add_f32_e32 v177, v148, v149
	v_or_b32_e32 v148, 16, v176
	v_ashrrev_i32_e32 v149, 31, v148
	v_lshlrev_b64 v[148:149], 6, v[148:149]
	v_lshl_add_u64 v[148:149], v[136:137], 0, v[148:149]
	ds_read_b128 v[166:169], v239 offset:1024
	s_waitcnt lgkmcnt(0)
	v_add_f32_e32 v148, v166, v167
	v_add_f32_e32 v149, v168, v169
	v_add_f32_e32 v178, v148, v149
	v_or_b32_e32 v148, 32, v176
	v_ashrrev_i32_e32 v149, 31, v148
	v_lshlrev_b64 v[148:149], 6, v[148:149]
	v_lshl_add_u64 v[148:149], v[136:137], 0, v[148:149]
	ds_read_b128 v[166:169], v239 offset:2048
	s_waitcnt lgkmcnt(0)
	v_add_f32_e32 v148, v166, v167
	v_add_f32_e32 v149, v168, v169
	v_add_f32_e32 v179, v148, v149
	v_or_b32_e32 v148, 48, v176
	v_ashrrev_i32_e32 v149, 31, v148
	v_lshlrev_b64 v[148:149], 6, v[148:149]
	v_lshl_add_u64 v[148:149], v[136:137], 0, v[148:149]
	ds_read_b128 v[166:169], v239 offset:3072
	s_waitcnt lgkmcnt(0)
	v_add_f32_e32 v148, v166, v167
	v_add_f32_e32 v149, v168, v169
	v_add_f32_e32 v180, v148, v149
	v_lshlrev_b64 v[148:149], 6, v[174:175]
	v_lshl_add_u64 v[148:149], v[136:137], 0, v[148:149]
	ds_read_b128 v[166:169], v239 offset:8192
	s_waitcnt lgkmcnt(0)
	v_add_f32_e32 v148, v166, v167
	v_add_f32_e32 v149, v168, v169
	v_add_f32_e32 v175, v148, v149
	v_lshlrev_b64 v[148:149], 6, v[172:173]
	v_lshl_add_u64 v[148:149], v[136:137], 0, v[148:149]
	ds_read_b128 v[166:169], v239 offset:9216
	s_waitcnt lgkmcnt(0)
	v_add_f32_e32 v148, v166, v167
	v_add_u32_e32 v166, 0xa0, v176
	v_add_f32_e32 v149, v168, v169
	v_ashrrev_i32_e32 v167, 31, v166
	v_add_f32_e32 v173, v148, v149
	v_lshlrev_b64 v[148:149], 6, v[166:167]
	v_lshl_add_u64 v[148:149], v[136:137], 0, v[148:149]
	ds_read_b128 v[168:171], v239 offset:10240
	s_waitcnt lgkmcnt(0)
	v_add_f32_e32 v148, v168, v169
	v_add_f32_e32 v149, v170, v171
	v_add_f32_e32 v167, v148, v149
	v_add_u32_e32 v148, 0xb0, v176
	v_ashrrev_i32_e32 v149, 31, v148
	v_lshlrev_b64 v[168:169], 6, v[148:149]
	v_lshl_add_u64 v[168:169], v[136:137], 0, v[168:169]
	ds_read_b128 v[168:171], v239 offset:11264
	s_waitcnt lgkmcnt(0)
	v_add_f32_e32 v149, v168, v169
	v_add_f32_e32 v168, v170, v171
	v_add_f32_e32 v149, v149, v168
	v_mov_b32_e32 v168, v201
	v_mov_b32_e32 v169, v201
	v_lshlrev_b32_e32 v168, 2, v168
	v_xor_b32_e32 v168, 64, v168
	v_mov_b32_e32 v168, v177
	s_nop 1
	v_permlane16_swap_b32_e32 v168, v177
	s_waitcnt lgkmcnt(0)
	v_add_f32_e32 v168, v177, v168
	v_lshlrev_b32_e32 v169, 2, v169
	v_xor_b32_e32 v169, 0x80, v169
	v_mov_b32_e32 v169, v168
	s_nop 1
	v_permlane32_swap_b32_e32 v169, v168
	s_waitcnt lgkmcnt(0)
	v_add_f32_e32 v168, v168, v169
	v_mov_b32_e32 v169, v201
	v_fmamk_f32 v168, v168, 0x3a800000, v202
	v_lshlrev_b32_e32 v169, 2, v169
	v_xor_b32_e32 v169, 64, v169
	v_mov_b32_e32 v169, v178
	s_nop 1
	v_permlane16_swap_b32_e32 v169, v178
	v_rsq_f32_e32 v168, v168
	s_waitcnt lgkmcnt(0)
	v_add_f32_e32 v212, v178, v169
	v_mov_b32_e32 v169, v201
	s_nop 0
	v_lshlrev_b32_e32 v169, 2, v169
	v_xor_b32_e32 v169, 0x80, v169
	v_mov_b32_e32 v213, v212
	s_nop 1
	v_permlane32_swap_b32_e32 v213, v212
	v_mov_b32_e32 v169, v201
	s_nop 0
	v_lshlrev_b32_e32 v169, 2, v169
	v_xor_b32_e32 v169, 64, v169
	v_mov_b32_e32 v169, v179
	s_nop 1
	v_permlane16_swap_b32_e32 v169, v179
	s_waitcnt lgkmcnt(0)
	v_add_f32_e32 v210, v179, v169
	v_mov_b32_e32 v169, v201
	s_nop 0
	v_lshlrev_b32_e32 v169, 2, v169
	v_xor_b32_e32 v169, 0x80, v169
	v_mov_b32_e32 v211, v210
	s_nop 1
	v_permlane32_swap_b32_e32 v211, v210
	v_mov_b32_e32 v169, v201
	s_nop 0
	v_lshlrev_b32_e32 v169, 2, v169
	v_xor_b32_e32 v169, 64, v169
	v_mov_b32_e32 v169, v180
	s_nop 1
	v_permlane16_swap_b32_e32 v169, v180
	s_waitcnt lgkmcnt(0)
; __device__ __forceinline__ float row_finish(float t) { t += shx(t, 16); t += shx(t, 32); return __builtin_amdgcn_rsqf(t * (1.0f / 1024.0f) + RMS_EPS); }
; __device__ __forceinline__ float sq4(f32x4 v) { return (v[0] * v[0] + v[1] * v[1]) + (v[2] * v[2] + v[3] * v[3]); }
;     __device__ __forceinline__ void operator()(const f32x4 (&acc)[2][2][4][2], const Unit& u, int wr, int wc, int fr, int fq) const {
;     ...
;             for (int m = 0; m < 4; ++m) rs[ai][m] = row_finish(rs[ai][m]);
; #pragma unroll
;         for (int ai = 0; ai < 2; ++ai)
; #pragma unroll
;             for (int m = 0; m < 4; ++m) {
;                 const int row = u.pm * BM + ai * HALF + wr * 64 + m * 16 + fr;
;                 const float rstd = rs[ai][m];
;                 f32x4 v[2][2];
; #pragma unroll
;                 for (int bj = 0; bj < 2; ++bj)
; #pragma unroll
;                     for (int n = 0; n < 2; ++n) v[bj][n] = acc[ai][bj][m][n] * rstd;
;                 if (mode == 2) {
;                     float q = (sq4(v[0][0]) + sq4(v[0][1])) + (sq4(v[1][0]) + sq4(v[1][1]));
;                     q += shx(q, 16); q += shx(q, 32);
;                     const float r2 = __builtin_amdgcn_rsqf(q * (1.0f / 64.0f) + RMS_EPS);
; #pragma unroll
;                     for (int bj = 0; bj < 2; ++bj)
; #pragma unroll
;                         for (int n = 0; n < 2; ++n) v[bj][n] = v[bj][n] * r2 * wv[bj][n];
	v_add_f32_e32 v208, v180, v169
	v_mov_b32_e32 v169, v201
	s_nop 0
	v_lshlrev_b32_e32 v169, 2, v169
	v_xor_b32_e32 v169, 0x80, v169
	v_mov_b32_e32 v209, v208
	s_nop 1
	v_permlane32_swap_b32_e32 v209, v208
	v_mov_b32_e32 v169, v201
	s_nop 0
	v_lshlrev_b32_e32 v169, 2, v169
	v_xor_b32_e32 v169, 64, v169
	v_mov_b32_e32 v169, v175
	s_nop 1
	v_permlane16_swap_b32_e32 v169, v175
	s_waitcnt lgkmcnt(0)
	v_add_f32_e32 v206, v175, v169
	v_mov_b32_e32 v169, v201
	s_nop 0
	v_lshlrev_b32_e32 v169, 2, v169
	v_xor_b32_e32 v169, 0x80, v169
	v_mov_b32_e32 v207, v206
	s_nop 1
	v_permlane32_swap_b32_e32 v207, v206
	v_mov_b32_e32 v169, v201
	s_nop 0
	v_lshlrev_b32_e32 v169, 2, v169
	v_xor_b32_e32 v169, 64, v169
	v_mov_b32_e32 v169, v173
	s_nop 1
	v_permlane16_swap_b32_e32 v169, v173
	s_waitcnt lgkmcnt(0)
	v_add_f32_e32 v177, v173, v169
	v_mov_b32_e32 v169, v201
	s_nop 0
	v_lshlrev_b32_e32 v169, 2, v169
	v_xor_b32_e32 v169, 0x80, v169
	v_mov_b32_e32 v205, v177
	s_nop 1
	v_permlane32_swap_b32_e32 v205, v177
	v_mov_b32_e32 v169, v201
	s_nop 0
	v_lshlrev_b32_e32 v169, 2, v169
	v_xor_b32_e32 v169, 64, v169
	v_mov_b32_e32 v169, v167
	s_nop 1
	v_permlane16_swap_b32_e32 v169, v167
	s_waitcnt lgkmcnt(0)
	v_add_f32_e32 v173, v167, v169
	v_mov_b32_e32 v167, v201
	v_pk_mul_f32 v[188:189], v[126:127], v[168:169] op_sel_hi:[1,0]
	v_lshlrev_b32_e32 v167, 2, v167
	v_xor_b32_e32 v167, 0x80, v167
	v_mov_b32_e32 v175, v173
	s_nop 1
	v_permlane32_swap_b32_e32 v175, v173
	v_mov_b32_e32 v167, v201
	v_pk_mul_f32 v[190:191], v[124:125], v[168:169] op_sel_hi:[1,0]
	v_lshlrev_b32_e32 v167, 2, v167
	v_xor_b32_e32 v167, 64, v167
	v_mov_b32_e32 v167, v149
	s_nop 1
	v_permlane16_swap_b32_e32 v167, v149
	v_pk_mul_f32 v[184:185], v[122:123], v[168:169] op_sel_hi:[1,0]
	v_pk_mul_f32 v[186:187], v[120:121], v[168:169] op_sel_hi:[1,0]
	v_pk_mul_f32 v[180:181], v[118:119], v[168:169] op_sel_hi:[1,0]
	v_pk_mul_f32 v[182:183], v[116:117], v[168:169] op_sel_hi:[1,0]
	s_waitcnt lgkmcnt(0)
	v_add_f32_e32 v149, v149, v167
	v_mov_b32_e32 v167, v201
	v_pk_mul_f32 v[178:179], v[114:115], v[168:169] op_sel_hi:[1,0]
	v_lshlrev_b32_e32 v167, 2, v167
	v_xor_b32_e32 v167, 0x80, v167
	v_mov_b32_e32 v167, v149
	s_nop 1
	v_permlane32_swap_b32_e32 v167, v149
	v_pk_mul_f32 v[170:171], v[112:113], v[168:169] op_sel_hi:[1,0]
	s_cbranch_vccnz .LBB0_1193
	v_mov_b32_e32 v114, v191
	v_mov_b32_e32 v115, v183
	v_mov_b32_e32 v112, v190
	v_mov_b32_e32 v113, v182
	v_pk_mul_f32 v[114:115], v[114:115], v[114:115]
	v_mov_b32_e32 v116, v189
	v_mov_b32_e32 v117, v181
	v_pk_fma_f32 v[112:113], v[112:113], v[112:113], v[114:115]
	v_mov_b32_e32 v114, v188
	v_mov_b32_e32 v115, v180
	v_pk_mul_f32 v[116:117], v[116:117], v[116:117]
	v_mov_b32_e32 v118, v185
	v_pk_fma_f32 v[114:115], v[114:115], v[114:115], v[116:117]
	v_mov_b32_e32 v116, v187
	v_mov_b32_e32 v117, v171
	v_pk_add_f32 v[112:113], v[112:113], v[114:115]
	v_mov_b32_e32 v114, v186
	v_mov_b32_e32 v115, v170
	v_pk_mul_f32 v[116:117], v[116:117], v[116:117]
	v_mov_b32_e32 v119, v179
	v_pk_fma_f32 v[114:115], v[114:115], v[114:115], v[116:117]
	v_mov_b32_e32 v116, v184
	v_mov_b32_e32 v117, v178
	v_pk_mul_f32 v[118:119], v[118:119], v[118:119]
	s_mov_b64 s[52:53], 0
	v_pk_fma_f32 v[116:117], v[116:117], v[116:117], v[118:119]
	s_nop 0
	v_pk_add_f32 v[114:115], v[114:115], v[116:117]
	s_nop 0
	v_pk_add_f32 v[112:113], v[112:113], v[114:115]
	s_nop 0
	v_add_f32_e32 v112, v112, v113
	v_mov_b32_e32 v113, v201
	s_nop 0
	v_lshlrev_b32_e32 v113, 2, v113
	v_xor_b32_e32 v113, 64, v113
	v_mov_b32_e32 v113, v112
	s_nop 1
	v_permlane16_swap_b32_e32 v113, v112
	s_waitcnt lgkmcnt(0)
	v_add_f32_e32 v112, v112, v113
	v_mov_b32_e32 v113, v201
	s_nop 0
	v_lshlrev_b32_e32 v113, 2, v113
	v_xor_b32_e32 v113, 0x80, v113
	v_mov_b32_e32 v113, v112
	s_nop 1
	v_permlane32_swap_b32_e32 v113, v112
	s_waitcnt lgkmcnt(0)
	v_add_f32_e32 v112, v112, v113
	v_fmamk_f32 v112, v112, 0x3c800000, v202
	v_rsq_f32_e32 v124, v112
	s_nop 0
	v_pk_mul_f32 v[112:113], v[190:191], v[124:125] op_sel_hi:[1,0]
	v_pk_mul_f32 v[114:115], v[188:189], v[124:125] op_sel_hi:[1,0]
	v_pk_mul_f32 v[116:117], v[186:187], v[124:125] op_sel_hi:[1,0]
	v_pk_mul_f32 v[118:119], v[184:185], v[124:125] op_sel_hi:[1,0]
	v_pk_mul_f32 v[120:121], v[182:183], v[124:125] op_sel_hi:[1,0]
	v_pk_mul_f32 v[122:123], v[180:181], v[124:125] op_sel_hi:[1,0]
	v_pk_mul_f32 v[168:169], v[170:171], v[124:125] op_sel_hi:[1,0]
	v_pk_mul_f32 v[124:125], v[178:179], v[124:125] op_sel_hi:[1,0]
	v_pk_mul_f32 v[114:115], v[156:157], v[114:115]
	v_pk_mul_f32 v[112:113], v[160:161], v[112:113]
	v_pk_mul_f32 v[118:119], v[150:151], v[118:119]
	v_pk_mul_f32 v[116:117], v[152:153], v[116:117]
	v_pk_mul_f32 v[122:123], v[162:163], v[122:123]
	v_pk_mul_f32 v[120:121], v[164:165], v[120:121]
	v_pk_mul_f32 v[126:127], v[154:155], v[124:125]
	v_pk_mul_f32 v[124:125], v[158:159], v[168:169]
